# plus: GLU epilogue aux loads hoisted, ssm pass-3 readout as two interleaved f32 MFMA chains with the LDS reads issued together
# speedup vs baseline: 1.0246x; 1.0012x over previous
; __device__ __forceinline__ f32x4 sigm4(f32x4 v) { return (f32x4){sigm(v[0]), sigm(v[1]), sigm(v[2]), sigm(v[3])}; }
; __device__ __forceinline__ u32x4 pack8(f32x4 a, f32x4 b) { u32x4 w; w.x = cvt_pk_bf16(a[0], a[1]); w.y = cvt_pk_bf16(a[2], a[3]); w.z = cvt_pk_bf16(b[0], b[1]); w.w = cvt_pk_bf16(b[2], b[3]); return w; }
; __device__ __forceinline__ void unpack8(u32x4 w, f32x4& a, f32x4& b) { a = (f32x4){bf_lo(w.x), bf_hi(w.x), bf_lo(w.y), bf_hi(w.y)}; b = (f32x4){bf_lo(w.z), bf_hi(w.z), bf_lo(w.w), bf_hi(w.w)}; }
;     __device__ __forceinline__ void operator()(const f32x4 (&acc)[2][2][4][2], const Unit& u, int wr, int wc, int fr, int fq) const {
;     ...
;         if (MODE == EP_GLU) {
; #pragma unroll
;             for (int bj = 0; bj < 2; ++bj) { cb0[bj] = *(const f32x4*)(bias + col0 + bj * HALF); cb1[bj] = *(const f32x4*)(bias + col0 + bj * HALF + 4); }
;         }
;     ...
;                     } else if (MODE == EP_GLU) {
;                         f32x4 y0, y1; unpack8(*(const u32x4*)(aux + row * ldaux + col), y0, y1);
;                         v0 = y0 * sigm4(v0 + cb0[bj]); v1 = y1 * sigm4(v1 + cb1[bj]);
;                         *(u32x4*)((bf16_t*)O + row * ldc + col) = pack8(v0, v1);
.LBB0_131:
	v_lshl_or_b32 v58, s41, 8, v172
	v_ashrrev_i32_e32 v59, 31, v58
	v_lshl_add_u64 v[62:63], v[58:59], 2, s[6:7]
	v_lshl_add_u32 v168, s40, 8, v170
	global_load_dwordx4 v[70:73], v[62:63], off
	global_load_dwordx4 v[66:69], v[62:63], off offset:16
	v_ashrrev_i32_e32 v169, 31, v168
	v_lshlrev_b64 v[60:61], 10, v[168:169]
	v_lshlrev_b64 v[156:157], 1, v[58:59]
	v_lshl_add_u64 v[58:59], s[14:15], 0, v[60:61]
	v_lshl_add_u64 v[178:179], v[58:59], 0, v[156:157]
	s_nop 0
	global_load_dwordx4 v[58:61], v[62:63], off offset:528
	s_nop 0
	global_load_dwordx4 v[62:65], v[62:63], off offset:512
	v_lshl_add_u32 v166, s40, 8, v170
	v_lshl_or_b32 v167, s41, 8, v172
	v_lshlrev_b32_e32 v167, 1, v167
	v_add_u32_e32 v199, 0, v166
	v_lshl_add_u32 v200, v199, 10, v167
	global_load_dwordx4 v[188:191], v200, s[14:15]
	global_load_dwordx4 v[212:215], v200, s[14:15] offset:256
	v_add_u32_e32 v199, 16, v166
	v_lshl_add_u32 v200, v199, 10, v167
	global_load_dwordx4 v[216:219], v200, s[14:15]
	global_load_dwordx4 v[220:223], v200, s[14:15] offset:256
	v_add_u32_e32 v199, 32, v166
	v_lshl_add_u32 v200, v199, 10, v167
	global_load_dwordx4 v[224:227], v200, s[14:15]
	global_load_dwordx4 v[228:231], v200, s[14:15] offset:256
	v_add_u32_e32 v199, 48, v166
	v_lshl_add_u32 v200, v199, 10, v167
	global_load_dwordx4 v[232:235], v200, s[14:15]
	global_load_dwordx4 v[236:239], v200, s[14:15] offset:256
	v_add_u32_e32 v199, 128, v166
	v_lshl_add_u32 v200, v199, 10, v167
	global_load_dwordx4 v[206:209], v200, s[14:15]
	global_load_dwordx4 v[246:249], v200, s[14:15] offset:256
	s_andn2_b64 vcc, exec, s[0:1]
	s_mov_b64 s[0:1], -1
	s_nop 0
	s_waitcnt vmcnt(10)
	v_pk_add_f32 v[144:145], v[144:145], v[72:73]
	v_pk_add_f32 v[142:143], v[142:143], v[70:71]
	v_pk_add_f32 v[138:139], v[138:139], v[66:67]
	v_pk_add_f32 v[140:141], v[140:141], v[68:69]
	v_mul_f32_e32 v180, 0xbfb8aa3b, v142
	v_mul_f32_e32 v181, 0xbfb8aa3b, v143
	v_mul_f32_e32 v182, 0xbfb8aa3b, v144
	v_mul_f32_e32 v183, 0xbfb8aa3b, v145
	v_mul_f32_e32 v184, 0xbfb8aa3b, v138
	v_mul_f32_e32 v185, 0xbfb8aa3b, v139
	v_mul_f32_e32 v186, 0xbfb8aa3b, v140
	v_mul_f32_e32 v187, 0xbfb8aa3b, v141
	s_waitcnt vmcnt(9)
	v_lshlrev_b32_e32 v138, 16, v188
	v_and_b32_e32 v139, 0xffff0000, v188
	v_lshlrev_b32_e32 v140, 16, v189
	v_and_b32_e32 v141, 0xffff0000, v189
	v_lshlrev_b32_e32 v142, 16, v190
	v_and_b32_e32 v143, 0xffff0000, v190
	v_lshlrev_b32_e32 v144, 16, v191
	v_and_b32_e32 v145, 0xffff0000, v191
	v_add_u32_e32 v199, 144, v166
	v_lshl_add_u32 v200, v199, 10, v167
	global_load_dwordx4 v[188:191], v200, s[14:15]
	v_exp_f32_e32 v174, v180
	v_exp_f32_e32 v175, v181
	v_exp_f32_e32 v176, v182
	v_exp_f32_e32 v177, v183
	v_exp_f32_e32 v180, v184
	v_exp_f32_e32 v181, v185
	v_exp_f32_e32 v182, v186
	v_exp_f32_e32 v183, v187
	v_add_f32_e32 v176, 1.0, v176
	v_add_f32_e32 v177, 1.0, v177
	v_add_f32_e32 v180, 1.0, v180
	v_add_f32_e32 v181, 1.0, v181
	v_add_f32_e32 v174, 1.0, v174
	v_add_f32_e32 v175, 1.0, v175
	v_add_f32_e32 v182, 1.0, v182
	v_add_f32_e32 v183, 1.0, v183
	v_rcp_f32_e32 v176, v176
	v_rcp_f32_e32 v177, v177
	v_rcp_f32_e32 v180, v180
	v_rcp_f32_e32 v181, v181
	v_rcp_f32_e32 v174, v174
	v_rcp_f32_e32 v175, v175
	v_rcp_f32_e32 v182, v182
	v_rcp_f32_e32 v183, v183
	v_pk_mul_f32 v[176:177], v[176:177], v[140:141]
	v_pk_mul_f32 v[142:143], v[180:181], v[142:143]
	v_pk_mul_f32 v[138:139], v[174:175], v[138:139]
	v_pk_mul_f32 v[144:145], v[182:183], v[144:145]
	v_cvt_pk_bf16_f32 v140, v138, v139
	v_cvt_pk_bf16_f32 v141, v176, v177
	v_cvt_pk_bf16_f32 v142, v142, v143
	v_pk_add_f32 v[136:137], v[136:137], v[64:65]
	v_cvt_pk_bf16_f32 v143, v144, v145
	s_nop 0
	v_pk_add_f32 v[134:135], v[134:135], v[62:63]
	v_pk_add_f32 v[132:133], v[132:133], v[60:61]
	v_pk_add_f32 v[130:131], v[130:131], v[58:59]
	v_mul_f32_e32 v134, 0xbfb8aa3b, v134
	v_mul_f32_e32 v135, 0xbfb8aa3b, v135
	v_mul_f32_e32 v136, 0xbfb8aa3b, v136
	v_mul_f32_e32 v137, 0xbfb8aa3b, v137
	v_mul_f32_e32 v130, 0xbfb8aa3b, v130
	v_mul_f32_e32 v131, 0xbfb8aa3b, v131
	v_mul_f32_e32 v132, 0xbfb8aa3b, v132
	v_mul_f32_e32 v133, 0xbfb8aa3b, v133
	v_exp_f32_e32 v134, v134
	v_exp_f32_e32 v135, v135
	v_exp_f32_e32 v136, v136
	v_exp_f32_e32 v137, v137
	v_exp_f32_e32 v130, v130
	v_exp_f32_e32 v131, v131
	v_exp_f32_e32 v132, v132
	v_exp_f32_e32 v133, v133
	v_lshlrev_b64 v[144:145], 12, v[168:169]
	v_add_f32_e32 v134, 1.0, v134
	v_add_f32_e32 v135, 1.0, v135
	v_add_f32_e32 v136, 1.0, v136
	v_add_f32_e32 v137, 1.0, v137
	v_add_f32_e32 v169, 1.0, v130
	v_add_f32_e32 v180, 1.0, v131
	v_add_f32_e32 v181, 1.0, v132
	v_add_f32_e32 v182, 1.0, v133
	v_or_b32_e32 v138, 16, v168
	v_rcp_f32_e32 v130, v134
	v_rcp_f32_e32 v131, v135
	v_rcp_f32_e32 v132, v136
	v_rcp_f32_e32 v133, v137
	v_rcp_f32_e32 v134, v169
	v_rcp_f32_e32 v135, v180
	v_rcp_f32_e32 v136, v181
	v_rcp_f32_e32 v137, v182
	v_ashrrev_i32_e32 v139, 31, v138
	v_lshl_add_u64 v[144:145], s[4:5], 0, v[144:145]
	v_lshlrev_b64 v[178:179], 10, v[138:139]
	v_lshl_add_u64 v[144:145], v[144:145], 0, v[156:157]
	v_lshl_add_u64 v[178:179], s[14:15], 0, v[178:179]
	global_store_dwordx4 v[144:145], v[140:143], off
	v_lshl_add_u64 v[178:179], v[178:179], 0, v[156:157]
	v_pk_add_f32 v[128:129], v[128:129], v[72:73]
	v_pk_add_f32 v[126:127], v[126:127], v[70:71]
	v_pk_add_f32 v[124:125], v[124:125], v[68:69]
	v_pk_add_f32 v[122:123], v[122:123], v[66:67]
	v_mul_f32_e32 v126, 0xbfb8aa3b, v126
	v_mul_f32_e32 v127, 0xbfb8aa3b, v127
	v_mul_f32_e32 v128, 0xbfb8aa3b, v128
	v_mul_f32_e32 v129, 0xbfb8aa3b, v129
	v_mul_f32_e32 v122, 0xbfb8aa3b, v122
	v_mul_f32_e32 v123, 0xbfb8aa3b, v123
	v_mul_f32_e32 v124, 0xbfb8aa3b, v124
	v_mul_f32_e32 v125, 0xbfb8aa3b, v125
	v_exp_f32_e32 v126, v126
	v_exp_f32_e32 v127, v127
	v_exp_f32_e32 v128, v128
	v_exp_f32_e32 v129, v129
	v_exp_f32_e32 v122, v122
	v_exp_f32_e32 v123, v123
	v_exp_f32_e32 v124, v124
	v_exp_f32_e32 v125, v125
	v_add_f32_e32 v126, 1.0, v126
	v_add_f32_e32 v127, 1.0, v127
	v_add_f32_e32 v128, 1.0, v128
	v_add_f32_e32 v129, 1.0, v129
	v_pk_add_f32 v[120:121], v[120:121], v[64:65]
	v_pk_add_f32 v[118:119], v[118:119], v[62:63]
	v_pk_add_f32 v[116:117], v[116:117], v[60:61]
	v_pk_add_f32 v[114:115], v[114:115], v[58:59]
	v_mul_f32_e32 v118, 0xbfb8aa3b, v118
	v_mul_f32_e32 v119, 0xbfb8aa3b, v119
	v_mul_f32_e32 v120, 0xbfb8aa3b, v120
	v_mul_f32_e32 v121, 0xbfb8aa3b, v121
	v_mul_f32_e32 v114, 0xbfb8aa3b, v114
	v_mul_f32_e32 v115, 0xbfb8aa3b, v115
	v_mul_f32_e32 v116, 0xbfb8aa3b, v116
	s_nop 0
	s_waitcnt vmcnt(10)
; __device__ __forceinline__ f32x4 sigm4(f32x4 v) { return (f32x4){sigm(v[0]), sigm(v[1]), sigm(v[2]), sigm(v[3])}; }
; __device__ __forceinline__ f32x4 gelu4(f32x4 v) { return (f32x4){gelu_t(v[0]), gelu_t(v[1]), gelu_t(v[2]), gelu_t(v[3])}; }
; __device__ __forceinline__ u32x4 pack8(f32x4 a, f32x4 b) { u32x4 w; w.x = cvt_pk_bf16(a[0], a[1]); w.y = cvt_pk_bf16(a[2], a[3]); w.z = cvt_pk_bf16(b[0], b[1]); w.w = cvt_pk_bf16(b[2], b[3]); return w; }
; __device__ __forceinline__ void unpack8(u32x4 w, f32x4& a, f32x4& b) { a = (f32x4){bf_lo(w.x), bf_hi(w.x), bf_lo(w.y), bf_hi(w.y)}; b = (f32x4){bf_lo(w.z), bf_hi(w.z), bf_lo(w.w), bf_hi(w.w)}; }
;     __device__ __forceinline__ void operator()(const f32x4 (&acc)[2][2][4][2], const Unit& u, int wr, int wc, int fr, int fq) const {
;     ...
; #pragma unroll
;         for (int ai = 0; ai < 2; ++ai)
; #pragma unroll
;             for (int m = 0; m < 4; ++m) {
;                 const size_t row = (size_t)(row0 + ai * HALF + m * 16);
;                 float ssq = 0.f;
; #pragma unroll
;                 for (int bj = 0; bj < 2; ++bj) {
;                     const int col = col0 + bj * HALF;
;                     f32x4 v0 = acc[ai][bj][m][0], v1 = acc[ai][bj][m][1];
;                     if (MODE == EP_INPROJ) {
;                         const float rs = rsr[ai][m];
;                         v0 = v0 * rs; v1 = v1 * rs;
;                         if (kind == 1) { v0 = gelu4(v0); v1 = gelu4(v1); }
;                         else if (kind == 2) { v0 = sigm4(v0 + cb0[bj]); v1 = sigm4(v1 + cb1[bj]); }
;                         *(u32x4*)((bf16_t*)O + row * ldc + col) = pack8(v0, v1);
;                     } else if (MODE == EP_GLU) {
;                         f32x4 y0, y1; unpack8(*(const u32x4*)(aux + row * ldaux + col), y0, y1);
;                         v0 = y0 * sigm4(v0 + cb0[bj]); v1 = y1 * sigm4(v1 + cb1[bj]);
;                         *(u32x4*)((bf16_t*)O + row * ldc + col) = pack8(v0, v1);
	v_lshlrev_b32_e32 v140, 16, v212
	v_and_b32_e32 v141, 0xffff0000, v212
	v_lshlrev_b32_e32 v142, 16, v213
	v_and_b32_e32 v143, 0xffff0000, v213
	v_lshlrev_b32_e32 v174, 16, v214
	v_and_b32_e32 v175, 0xffff0000, v214
	v_lshlrev_b32_e32 v176, 16, v215
	v_and_b32_e32 v177, 0xffff0000, v215
	v_add_u32_e32 v199, 144, v166
	v_lshl_add_u32 v200, v199, 10, v167
	global_load_dwordx4 v[212:215], v200, s[14:15] offset:256
	v_pk_mul_f32 v[132:133], v[132:133], v[142:143]
	v_pk_mul_f32 v[130:131], v[130:131], v[140:141]
	v_pk_mul_f32 v[136:137], v[136:137], v[176:177]
	v_pk_mul_f32 v[134:135], v[134:135], v[174:175]
	v_cvt_pk_bf16_f32 v130, v130, v131
	v_cvt_pk_bf16_f32 v131, v132, v133
	v_add_f32_e32 v140, 1.0, v122
	v_cvt_pk_bf16_f32 v132, v134, v135
	v_cvt_pk_bf16_f32 v133, v136, v137
	s_nop 0
	v_add_f32_e32 v141, 1.0, v123
	v_add_f32_e32 v142, 1.0, v124
	v_add_f32_e32 v143, 1.0, v125
	v_rcp_f32_e32 v122, v126
	v_rcp_f32_e32 v123, v127
	v_rcp_f32_e32 v124, v128
	v_rcp_f32_e32 v125, v129
	v_rcp_f32_e32 v126, v140
	v_rcp_f32_e32 v127, v141
	v_rcp_f32_e32 v128, v142
	v_rcp_f32_e32 v129, v143
	global_store_dwordx4 v[144:145], v[130:133], off offset:256
	v_mul_f32_e32 v117, 0xbfb8aa3b, v117
	v_exp_f32_e32 v118, v118
	v_exp_f32_e32 v119, v119
	v_exp_f32_e32 v120, v120
	v_exp_f32_e32 v121, v121
	v_exp_f32_e32 v114, v114
	v_exp_f32_e32 v115, v115
	v_exp_f32_e32 v116, v116
	v_exp_f32_e32 v117, v117
	v_add_f32_e32 v118, 1.0, v118
	v_add_f32_e32 v119, 1.0, v119
	v_add_f32_e32 v120, 1.0, v120
	v_add_f32_e32 v121, 1.0, v121
	v_pk_add_f32 v[112:113], v[112:113], v[72:73]
	v_pk_add_f32 v[110:111], v[110:111], v[70:71]
	v_pk_add_f32 v[108:109], v[108:109], v[68:69]
	v_pk_add_f32 v[106:107], v[106:107], v[66:67]
	v_mul_f32_e32 v110, 0xbfb8aa3b, v110
	v_mul_f32_e32 v111, 0xbfb8aa3b, v111
	v_mul_f32_e32 v112, 0xbfb8aa3b, v112
	v_mul_f32_e32 v113, 0xbfb8aa3b, v113
	v_mul_f32_e32 v106, 0xbfb8aa3b, v106
	v_mul_f32_e32 v107, 0xbfb8aa3b, v107
	v_mul_f32_e32 v108, 0xbfb8aa3b, v108
	v_mul_f32_e32 v109, 0xbfb8aa3b, v109
	v_exp_f32_e32 v110, v110
	v_exp_f32_e32 v111, v111
	v_exp_f32_e32 v112, v112
	v_exp_f32_e32 v113, v113
	v_exp_f32_e32 v106, v106
	v_exp_f32_e32 v107, v107
	v_exp_f32_e32 v108, v108
	v_exp_f32_e32 v109, v109
	v_add_f32_e32 v110, 1.0, v110
	v_add_f32_e32 v111, 1.0, v111
	v_add_f32_e32 v112, 1.0, v112
	v_add_f32_e32 v113, 1.0, v113
	v_pk_add_f32 v[104:105], v[104:105], v[64:65]
	v_pk_add_f32 v[102:103], v[102:103], v[62:63]
	v_pk_add_f32 v[100:101], v[100:101], v[60:61]
	v_pk_add_f32 v[98:99], v[98:99], v[58:59]
	v_mul_f32_e32 v102, 0xbfb8aa3b, v102
	v_mul_f32_e32 v103, 0xbfb8aa3b, v103
	v_mul_f32_e32 v104, 0xbfb8aa3b, v104
	v_mul_f32_e32 v105, 0xbfb8aa3b, v105
	v_mul_f32_e32 v98, 0xbfb8aa3b, v98
	v_mul_f32_e32 v99, 0xbfb8aa3b, v99
	v_mul_f32_e32 v100, 0xbfb8aa3b, v100
	v_mul_f32_e32 v101, 0xbfb8aa3b, v101
	v_exp_f32_e32 v102, v102
	v_exp_f32_e32 v103, v103
	v_exp_f32_e32 v104, v104
	v_exp_f32_e32 v105, v105
	v_exp_f32_e32 v98, v98
	v_exp_f32_e32 v99, v99
	v_exp_f32_e32 v100, v100
	v_exp_f32_e32 v101, v101
	v_add_f32_e32 v102, 1.0, v102
	v_add_f32_e32 v103, 1.0, v103
	v_add_f32_e32 v104, 1.0, v104
	v_add_f32_e32 v105, 1.0, v105
	v_pk_add_f32 v[96:97], v[96:97], v[72:73]
	v_pk_add_f32 v[94:95], v[94:95], v[70:71]
	v_pk_add_f32 v[92:93], v[92:93], v[68:69]
	v_pk_add_f32 v[90:91], v[90:91], v[66:67]
	v_mul_f32_e32 v94, 0xbfb8aa3b, v94
	v_mul_f32_e32 v95, 0xbfb8aa3b, v95
	s_nop 0
	s_waitcnt vmcnt(11)
	v_lshlrev_b32_e32 v130, 16, v216
	v_and_b32_e32 v131, 0xffff0000, v216
	v_lshlrev_b32_e32 v132, 16, v217
	v_and_b32_e32 v133, 0xffff0000, v217
	v_lshlrev_b32_e32 v134, 16, v218
	v_and_b32_e32 v135, 0xffff0000, v218
	v_lshlrev_b32_e32 v136, 16, v219
	v_and_b32_e32 v137, 0xffff0000, v219
	v_add_u32_e32 v199, 160, v166
	v_lshl_add_u32 v200, v199, 10, v167
	global_load_dwordx4 v[216:219], v200, s[14:15]
	v_pk_mul_f32 v[128:129], v[128:129], v[136:137]
	v_pk_mul_f32 v[126:127], v[126:127], v[134:135]
	v_pk_mul_f32 v[132:133], v[124:125], v[132:133]
	v_pk_mul_f32 v[122:123], v[122:123], v[130:131]
	v_add_f32_e32 v136, 1.0, v114
	v_cvt_pk_bf16_f32 v124, v122, v123
	v_cvt_pk_bf16_f32 v125, v132, v133
	v_cvt_pk_bf16_f32 v126, v126, v127
	v_cvt_pk_bf16_f32 v127, v128, v129
	s_nop 0
	v_lshlrev_b64 v[132:133], 12, v[138:139]
	v_add_f32_e32 v137, 1.0, v115
	v_add_f32_e32 v138, 1.0, v116
	v_add_f32_e32 v139, 1.0, v117
	v_or_b32_e32 v122, 32, v168
	v_rcp_f32_e32 v114, v118
	v_rcp_f32_e32 v115, v119
	v_rcp_f32_e32 v116, v120
	v_rcp_f32_e32 v117, v121
	v_rcp_f32_e32 v118, v136
	v_rcp_f32_e32 v119, v137
	v_rcp_f32_e32 v120, v138
	v_rcp_f32_e32 v121, v139
	v_ashrrev_i32_e32 v123, 31, v122
	v_lshl_add_u64 v[132:133], s[4:5], 0, v[132:133]
	v_lshlrev_b64 v[134:135], 10, v[122:123]
	v_lshl_add_u64 v[132:133], v[132:133], 0, v[156:157]
	v_lshl_add_u64 v[134:135], s[14:15], 0, v[134:135]
	global_store_dwordx4 v[132:133], v[124:127], off
	v_lshl_add_u64 v[134:135], v[134:135], 0, v[156:157]
	v_mul_f32_e32 v96, 0xbfb8aa3b, v96
	v_mul_f32_e32 v97, 0xbfb8aa3b, v97
	v_mul_f32_e32 v90, 0xbfb8aa3b, v90
	v_mul_f32_e32 v91, 0xbfb8aa3b, v91
	v_mul_f32_e32 v92, 0xbfb8aa3b, v92
	v_mul_f32_e32 v93, 0xbfb8aa3b, v93
	v_exp_f32_e32 v94, v94
	v_exp_f32_e32 v95, v95
	v_exp_f32_e32 v96, v96
	v_exp_f32_e32 v97, v97
	v_exp_f32_e32 v90, v90
	v_exp_f32_e32 v91, v91
	v_exp_f32_e32 v92, v92
	v_exp_f32_e32 v93, v93
	v_add_f32_e32 v94, 1.0, v94
	v_add_f32_e32 v95, 1.0, v95
	v_add_f32_e32 v96, 1.0, v96
	v_add_f32_e32 v97, 1.0, v97
	v_pk_add_f32 v[88:89], v[88:89], v[64:65]
	v_pk_add_f32 v[86:87], v[86:87], v[62:63]
	v_pk_add_f32 v[84:85], v[84:85], v[60:61]
	v_pk_add_f32 v[82:83], v[82:83], v[58:59]
	v_mul_f32_e32 v86, 0xbfb8aa3b, v86
	v_mul_f32_e32 v87, 0xbfb8aa3b, v87
	v_mul_f32_e32 v88, 0xbfb8aa3b, v88
	v_mul_f32_e32 v89, 0xbfb8aa3b, v89
	v_mul_f32_e32 v82, 0xbfb8aa3b, v82
	v_mul_f32_e32 v83, 0xbfb8aa3b, v83
	v_mul_f32_e32 v84, 0xbfb8aa3b, v84
	v_mul_f32_e32 v85, 0xbfb8aa3b, v85
	v_exp_f32_e32 v86, v86
	v_exp_f32_e32 v87, v87
	v_exp_f32_e32 v88, v88
	v_exp_f32_e32 v89, v89
	v_exp_f32_e32 v82, v82
	v_exp_f32_e32 v83, v83
	v_exp_f32_e32 v84, v84
	v_exp_f32_e32 v85, v85
	v_add_f32_e32 v86, 1.0, v86
	v_add_f32_e32 v87, 1.0, v87
	v_add_f32_e32 v88, 1.0, v88
	v_add_f32_e32 v89, 1.0, v89
	v_pk_add_f32 v[80:81], v[80:81], v[72:73]
	v_pk_add_f32 v[78:79], v[78:79], v[70:71]
	v_pk_add_f32 v[76:77], v[76:77], v[68:69]
	v_pk_add_f32 v[74:75], v[74:75], v[66:67]
	v_mul_f32_e32 v78, 0xbfb8aa3b, v78
	v_mul_f32_e32 v79, 0xbfb8aa3b, v79
	v_mul_f32_e32 v80, 0xbfb8aa3b, v80
	v_mul_f32_e32 v81, 0xbfb8aa3b, v81
	v_mul_f32_e32 v74, 0xbfb8aa3b, v74
	v_mul_f32_e32 v75, 0xbfb8aa3b, v75
	v_mul_f32_e32 v76, 0xbfb8aa3b, v76
	v_mul_f32_e32 v77, 0xbfb8aa3b, v77
	v_exp_f32_e32 v78, v78
	v_exp_f32_e32 v79, v79
	v_exp_f32_e32 v80, v80
	v_exp_f32_e32 v81, v81
	v_exp_f32_e32 v74, v74
	s_nop 0
	s_waitcnt vmcnt(12)
; __device__ __forceinline__ f32x4 sigm4(f32x4 v) { return (f32x4){sigm(v[0]), sigm(v[1]), sigm(v[2]), sigm(v[3])}; }
; __device__ __forceinline__ f32x4 gelu4(f32x4 v) { return (f32x4){gelu_t(v[0]), gelu_t(v[1]), gelu_t(v[2]), gelu_t(v[3])}; }
; __device__ __forceinline__ u32x4 pack8(f32x4 a, f32x4 b) { u32x4 w; w.x = cvt_pk_bf16(a[0], a[1]); w.y = cvt_pk_bf16(a[2], a[3]); w.z = cvt_pk_bf16(b[0], b[1]); w.w = cvt_pk_bf16(b[2], b[3]); return w; }
; __device__ __forceinline__ void unpack8(u32x4 w, f32x4& a, f32x4& b) { a = (f32x4){bf_lo(w.x), bf_hi(w.x), bf_lo(w.y), bf_hi(w.y)}; b = (f32x4){bf_lo(w.z), bf_hi(w.z), bf_lo(w.w), bf_hi(w.w)}; }
;     __device__ __forceinline__ void operator()(const f32x4 (&acc)[2][2][4][2], const Unit& u, int wr, int wc, int fr, int fq) const {
;     ...
; #pragma unroll
;         for (int ai = 0; ai < 2; ++ai)
; #pragma unroll
;             for (int m = 0; m < 4; ++m) {
;                 const size_t row = (size_t)(row0 + ai * HALF + m * 16);
;                 float ssq = 0.f;
; #pragma unroll
;                 for (int bj = 0; bj < 2; ++bj) {
;                     const int col = col0 + bj * HALF;
;                     f32x4 v0 = acc[ai][bj][m][0], v1 = acc[ai][bj][m][1];
;                     if (MODE == EP_INPROJ) {
;                         const float rs = rsr[ai][m];
;                         v0 = v0 * rs; v1 = v1 * rs;
;                         if (kind == 1) { v0 = gelu4(v0); v1 = gelu4(v1); }
;                         else if (kind == 2) { v0 = sigm4(v0 + cb0[bj]); v1 = sigm4(v1 + cb1[bj]); }
;                         *(u32x4*)((bf16_t*)O + row * ldc + col) = pack8(v0, v1);
;                     } else if (MODE == EP_GLU) {
;                         f32x4 y0, y1; unpack8(*(const u32x4*)(aux + row * ldaux + col), y0, y1);
;                         v0 = y0 * sigm4(v0 + cb0[bj]); v1 = y1 * sigm4(v1 + cb1[bj]);
;                         *(u32x4*)((bf16_t*)O + row * ldc + col) = pack8(v0, v1);
	v_lshlrev_b32_e32 v124, 16, v220
	v_and_b32_e32 v125, 0xffff0000, v220
	v_lshlrev_b32_e32 v126, 16, v221
	v_and_b32_e32 v127, 0xffff0000, v221
	v_lshlrev_b32_e32 v128, 16, v222
	v_and_b32_e32 v129, 0xffff0000, v222
	v_lshlrev_b32_e32 v130, 16, v223
	v_and_b32_e32 v131, 0xffff0000, v223
	v_add_u32_e32 v199, 160, v166
	v_lshl_add_u32 v200, v199, 10, v167
	global_load_dwordx4 v[220:223], v200, s[14:15] offset:256
	v_pk_mul_f32 v[116:117], v[116:117], v[126:127]
	v_pk_mul_f32 v[114:115], v[114:115], v[124:125]
	v_pk_mul_f32 v[120:121], v[120:121], v[130:131]
	v_pk_mul_f32 v[118:119], v[118:119], v[128:129]
	v_cvt_pk_bf16_f32 v114, v114, v115
	v_cvt_pk_bf16_f32 v115, v116, v117
	v_add_f32_e32 v124, 1.0, v106
	v_cvt_pk_bf16_f32 v116, v118, v119
	v_cvt_pk_bf16_f32 v117, v120, v121
	s_nop 0
	v_add_f32_e32 v125, 1.0, v107
	v_add_f32_e32 v126, 1.0, v108
	v_add_f32_e32 v127, 1.0, v109
	v_rcp_f32_e32 v106, v110
	v_rcp_f32_e32 v107, v111
	v_rcp_f32_e32 v108, v112
	v_rcp_f32_e32 v109, v113
	v_rcp_f32_e32 v110, v124
	v_rcp_f32_e32 v111, v125
	v_rcp_f32_e32 v112, v126
	v_rcp_f32_e32 v113, v127
	global_store_dwordx4 v[132:133], v[114:117], off offset:256
	v_exp_f32_e32 v75, v75
	v_exp_f32_e32 v76, v76
	v_exp_f32_e32 v77, v77
	v_add_f32_e32 v78, 1.0, v78
	v_add_f32_e32 v79, 1.0, v79
	v_add_f32_e32 v80, 1.0, v80
	v_add_f32_e32 v81, 1.0, v81
	v_pk_add_f32 v[56:57], v[56:57], v[64:65]
	v_pk_add_f32 v[54:55], v[54:55], v[62:63]
	v_pk_add_f32 v[52:53], v[52:53], v[60:61]
	v_pk_add_f32 v[50:51], v[50:51], v[58:59]
	v_mul_f32_e32 v54, 0xbfb8aa3b, v54
	v_mul_f32_e32 v55, 0xbfb8aa3b, v55
	v_mul_f32_e32 v56, 0xbfb8aa3b, v56
	v_mul_f32_e32 v57, 0xbfb8aa3b, v57
	v_mul_f32_e32 v50, 0xbfb8aa3b, v50
	v_mul_f32_e32 v51, 0xbfb8aa3b, v51
	v_mul_f32_e32 v52, 0xbfb8aa3b, v52
	v_mul_f32_e32 v53, 0xbfb8aa3b, v53
	v_exp_f32_e32 v54, v54
	v_exp_f32_e32 v55, v55
	v_exp_f32_e32 v56, v56
	v_exp_f32_e32 v57, v57
	v_exp_f32_e32 v50, v50
	v_exp_f32_e32 v51, v51
	v_exp_f32_e32 v52, v52
	v_exp_f32_e32 v53, v53
	v_add_f32_e32 v54, 1.0, v54
	v_add_f32_e32 v55, 1.0, v55
	v_add_f32_e32 v56, 1.0, v56
	v_add_f32_e32 v57, 1.0, v57
	v_pk_add_f32 v[48:49], v[48:49], v[72:73]
	v_pk_add_f32 v[46:47], v[46:47], v[70:71]
	v_pk_add_f32 v[44:45], v[44:45], v[68:69]
	v_pk_add_f32 v[42:43], v[42:43], v[66:67]
	v_mul_f32_e32 v46, 0xbfb8aa3b, v46
	v_mul_f32_e32 v47, 0xbfb8aa3b, v47
	v_mul_f32_e32 v48, 0xbfb8aa3b, v48
	v_mul_f32_e32 v49, 0xbfb8aa3b, v49
	v_mul_f32_e32 v42, 0xbfb8aa3b, v42
	v_mul_f32_e32 v43, 0xbfb8aa3b, v43
	v_mul_f32_e32 v44, 0xbfb8aa3b, v44
	v_mul_f32_e32 v45, 0xbfb8aa3b, v45
	v_exp_f32_e32 v46, v46
	v_exp_f32_e32 v47, v47
	v_exp_f32_e32 v48, v48
	v_exp_f32_e32 v49, v49
	v_exp_f32_e32 v42, v42
	v_exp_f32_e32 v43, v43
	v_exp_f32_e32 v44, v44
	v_exp_f32_e32 v45, v45
	v_add_f32_e32 v46, 1.0, v46
	v_add_f32_e32 v47, 1.0, v47
	v_add_f32_e32 v48, 1.0, v48
	v_add_f32_e32 v49, 1.0, v49
	v_pk_add_f32 v[40:41], v[40:41], v[64:65]
	v_pk_add_f32 v[38:39], v[38:39], v[62:63]
	v_pk_add_f32 v[36:37], v[36:37], v[60:61]
	v_pk_add_f32 v[34:35], v[34:35], v[58:59]
	v_mul_f32_e32 v38, 0xbfb8aa3b, v38
	v_mul_f32_e32 v39, 0xbfb8aa3b, v39
	v_mul_f32_e32 v40, 0xbfb8aa3b, v40
	v_mul_f32_e32 v41, 0xbfb8aa3b, v41
	v_mul_f32_e32 v34, 0xbfb8aa3b, v34
	v_mul_f32_e32 v35, 0xbfb8aa3b, v35
	v_mul_f32_e32 v36, 0xbfb8aa3b, v36
	v_mul_f32_e32 v37, 0xbfb8aa3b, v37
	s_nop 0
	s_waitcnt vmcnt(13)
	v_lshlrev_b32_e32 v114, 16, v224
	v_and_b32_e32 v115, 0xffff0000, v224
	v_lshlrev_b32_e32 v116, 16, v225
	v_and_b32_e32 v117, 0xffff0000, v225
	v_lshlrev_b32_e32 v118, 16, v226
	v_and_b32_e32 v119, 0xffff0000, v226
	v_lshlrev_b32_e32 v120, 16, v227
	v_and_b32_e32 v121, 0xffff0000, v227
	v_add_u32_e32 v199, 176, v166
	v_lshl_add_u32 v200, v199, 10, v167
	global_load_dwordx4 v[224:227], v200, s[14:15]
	v_pk_mul_f32 v[112:113], v[112:113], v[120:121]
	v_pk_mul_f32 v[110:111], v[110:111], v[118:119]
	v_pk_mul_f32 v[116:117], v[108:109], v[116:117]
	v_pk_mul_f32 v[106:107], v[106:107], v[114:115]
	v_add_f32_e32 v120, 1.0, v98
	v_cvt_pk_bf16_f32 v108, v106, v107
	v_cvt_pk_bf16_f32 v109, v116, v117
	v_cvt_pk_bf16_f32 v110, v110, v111
	v_cvt_pk_bf16_f32 v111, v112, v113
	s_nop 0
	v_lshlrev_b64 v[116:117], 12, v[122:123]
	v_add_f32_e32 v121, 1.0, v99
	v_add_f32_e32 v122, 1.0, v100
	v_add_f32_e32 v123, 1.0, v101
	v_or_b32_e32 v106, 48, v168
	v_rcp_f32_e32 v98, v102
	v_rcp_f32_e32 v99, v103
	v_rcp_f32_e32 v100, v104
	v_rcp_f32_e32 v101, v105
	v_rcp_f32_e32 v102, v120
	v_rcp_f32_e32 v103, v121
	v_rcp_f32_e32 v104, v122
	v_rcp_f32_e32 v105, v123
	v_ashrrev_i32_e32 v107, 31, v106
	v_lshl_add_u64 v[116:117], s[4:5], 0, v[116:117]
	v_lshlrev_b64 v[118:119], 10, v[106:107]
	v_lshl_add_u64 v[116:117], v[116:117], 0, v[156:157]
	v_lshl_add_u64 v[118:119], s[14:15], 0, v[118:119]
	global_store_dwordx4 v[116:117], v[108:111], off
	v_lshl_add_u64 v[118:119], v[118:119], 0, v[156:157]
	v_exp_f32_e32 v38, v38
	v_exp_f32_e32 v39, v39
	v_exp_f32_e32 v40, v40
	v_exp_f32_e32 v41, v41
	v_exp_f32_e32 v34, v34
	v_exp_f32_e32 v35, v35
	v_exp_f32_e32 v36, v36
	v_exp_f32_e32 v37, v37
	v_add_f32_e32 v38, 1.0, v38
	v_add_f32_e32 v39, 1.0, v39
	v_add_f32_e32 v40, 1.0, v40
	v_add_f32_e32 v41, 1.0, v41
	v_pk_add_f32 v[32:33], v[32:33], v[72:73]
	v_pk_add_f32 v[30:31], v[30:31], v[70:71]
	v_pk_add_f32 v[28:29], v[28:29], v[68:69]
	v_pk_add_f32 v[26:27], v[26:27], v[66:67]
	v_mul_f32_e32 v30, 0xbfb8aa3b, v30
	v_mul_f32_e32 v31, 0xbfb8aa3b, v31
	v_mul_f32_e32 v32, 0xbfb8aa3b, v32
	v_mul_f32_e32 v33, 0xbfb8aa3b, v33
	v_mul_f32_e32 v26, 0xbfb8aa3b, v26
	v_mul_f32_e32 v27, 0xbfb8aa3b, v27
	v_mul_f32_e32 v28, 0xbfb8aa3b, v28
	v_mul_f32_e32 v29, 0xbfb8aa3b, v29
	v_exp_f32_e32 v30, v30
	v_exp_f32_e32 v31, v31
	v_exp_f32_e32 v32, v32
	v_exp_f32_e32 v33, v33
	v_exp_f32_e32 v26, v26
	v_exp_f32_e32 v27, v27
	v_exp_f32_e32 v28, v28
	v_exp_f32_e32 v29, v29
	v_add_f32_e32 v30, 1.0, v30
	v_add_f32_e32 v31, 1.0, v31
	v_add_f32_e32 v32, 1.0, v32
	v_add_f32_e32 v33, 1.0, v33
	v_pk_add_f32 v[24:25], v[24:25], v[64:65]
	v_pk_add_f32 v[22:23], v[22:23], v[62:63]
	v_pk_add_f32 v[20:21], v[20:21], v[60:61]
	v_pk_add_f32 v[18:19], v[18:19], v[58:59]
	v_mul_f32_e32 v22, 0xbfb8aa3b, v22
	v_mul_f32_e32 v23, 0xbfb8aa3b, v23
	v_mul_f32_e32 v24, 0xbfb8aa3b, v24
	v_mul_f32_e32 v25, 0xbfb8aa3b, v25
	v_mul_f32_e32 v18, 0xbfb8aa3b, v18
	v_mul_f32_e32 v19, 0xbfb8aa3b, v19
	v_mul_f32_e32 v20, 0xbfb8aa3b, v20
	v_mul_f32_e32 v21, 0xbfb8aa3b, v21
	v_exp_f32_e32 v22, v22
	v_exp_f32_e32 v23, v23
	v_exp_f32_e32 v24, v24
	v_exp_f32_e32 v25, v25
	v_exp_f32_e32 v18, v18
	v_exp_f32_e32 v19, v19
	v_exp_f32_e32 v20, v20
	v_exp_f32_e32 v21, v21
	v_add_f32_e32 v22, 1.0, v22
	v_add_f32_e32 v23, 1.0, v23
	v_add_f32_e32 v24, 1.0, v24
	s_nop 0
	s_waitcnt vmcnt(14)
; __device__ __forceinline__ f32x4 sigm4(f32x4 v) { return (f32x4){sigm(v[0]), sigm(v[1]), sigm(v[2]), sigm(v[3])}; }
; __device__ __forceinline__ f32x4 gelu4(f32x4 v) { return (f32x4){gelu_t(v[0]), gelu_t(v[1]), gelu_t(v[2]), gelu_t(v[3])}; }
; __device__ __forceinline__ u32x4 pack8(f32x4 a, f32x4 b) { u32x4 w; w.x = cvt_pk_bf16(a[0], a[1]); w.y = cvt_pk_bf16(a[2], a[3]); w.z = cvt_pk_bf16(b[0], b[1]); w.w = cvt_pk_bf16(b[2], b[3]); return w; }
; __device__ __forceinline__ void unpack8(u32x4 w, f32x4& a, f32x4& b) { a = (f32x4){bf_lo(w.x), bf_hi(w.x), bf_lo(w.y), bf_hi(w.y)}; b = (f32x4){bf_lo(w.z), bf_hi(w.z), bf_lo(w.w), bf_hi(w.w)}; }
;     __device__ __forceinline__ void operator()(const f32x4 (&acc)[2][2][4][2], const Unit& u, int wr, int wc, int fr, int fq) const {
;     ...
; #pragma unroll
;         for (int ai = 0; ai < 2; ++ai)
; #pragma unroll
;             for (int m = 0; m < 4; ++m) {
;                 const size_t row = (size_t)(row0 + ai * HALF + m * 16);
;                 float ssq = 0.f;
; #pragma unroll
;                 for (int bj = 0; bj < 2; ++bj) {
;                     const int col = col0 + bj * HALF;
;                     f32x4 v0 = acc[ai][bj][m][0], v1 = acc[ai][bj][m][1];
;                     if (MODE == EP_INPROJ) {
;                         const float rs = rsr[ai][m];
;                         v0 = v0 * rs; v1 = v1 * rs;
;                         if (kind == 1) { v0 = gelu4(v0); v1 = gelu4(v1); }
;                         else if (kind == 2) { v0 = sigm4(v0 + cb0[bj]); v1 = sigm4(v1 + cb1[bj]); }
;                         *(u32x4*)((bf16_t*)O + row * ldc + col) = pack8(v0, v1);
;                     } else if (MODE == EP_GLU) {
;                         f32x4 y0, y1; unpack8(*(const u32x4*)(aux + row * ldaux + col), y0, y1);
;                         v0 = y0 * sigm4(v0 + cb0[bj]); v1 = y1 * sigm4(v1 + cb1[bj]);
;                         *(u32x4*)((bf16_t*)O + row * ldc + col) = pack8(v0, v1);
	v_lshlrev_b32_e32 v108, 16, v228
	v_and_b32_e32 v109, 0xffff0000, v228
	v_lshlrev_b32_e32 v110, 16, v229
	v_and_b32_e32 v111, 0xffff0000, v229
	v_lshlrev_b32_e32 v112, 16, v230
	v_and_b32_e32 v113, 0xffff0000, v230
	v_lshlrev_b32_e32 v114, 16, v231
	v_and_b32_e32 v115, 0xffff0000, v231
	v_add_u32_e32 v199, 176, v166
	v_lshl_add_u32 v200, v199, 10, v167
	global_load_dwordx4 v[228:231], v200, s[14:15] offset:256
	v_pk_mul_f32 v[100:101], v[100:101], v[110:111]
	v_pk_mul_f32 v[98:99], v[98:99], v[108:109]
	v_pk_mul_f32 v[104:105], v[104:105], v[114:115]
	v_pk_mul_f32 v[102:103], v[102:103], v[112:113]
	v_cvt_pk_bf16_f32 v98, v98, v99
	v_cvt_pk_bf16_f32 v99, v100, v101
	v_add_f32_e32 v108, 1.0, v90
	v_cvt_pk_bf16_f32 v100, v102, v103
	v_cvt_pk_bf16_f32 v101, v104, v105
	s_nop 0
	v_add_f32_e32 v109, 1.0, v91
	v_add_f32_e32 v110, 1.0, v92
	v_add_f32_e32 v111, 1.0, v93
	v_rcp_f32_e32 v90, v94
	v_rcp_f32_e32 v91, v95
	v_rcp_f32_e32 v92, v96
	v_rcp_f32_e32 v93, v97
	v_rcp_f32_e32 v94, v108
	v_rcp_f32_e32 v95, v109
	v_rcp_f32_e32 v96, v110
	v_rcp_f32_e32 v97, v111
	global_store_dwordx4 v[116:117], v[98:101], off offset:256
	v_add_f32_e32 v25, 1.0, v25
	v_pk_add_f32 v[16:17], v[16:17], v[72:73]
	v_pk_add_f32 v[14:15], v[14:15], v[70:71]
	v_pk_add_f32 v[12:13], v[12:13], v[68:69]
	v_pk_add_f32 v[10:11], v[10:11], v[66:67]
	v_mul_f32_e32 v14, 0xbfb8aa3b, v14
	v_mul_f32_e32 v15, 0xbfb8aa3b, v15
	v_mul_f32_e32 v16, 0xbfb8aa3b, v16
	v_mul_f32_e32 v17, 0xbfb8aa3b, v17
	v_mul_f32_e32 v10, 0xbfb8aa3b, v10
	v_mul_f32_e32 v11, 0xbfb8aa3b, v11
	v_mul_f32_e32 v12, 0xbfb8aa3b, v12
	v_mul_f32_e32 v13, 0xbfb8aa3b, v13
	v_exp_f32_e32 v14, v14
	v_exp_f32_e32 v15, v15
	v_exp_f32_e32 v16, v16
	v_exp_f32_e32 v17, v17
	v_exp_f32_e32 v10, v10
	v_exp_f32_e32 v11, v11
	v_exp_f32_e32 v12, v12
	v_exp_f32_e32 v13, v13
	v_add_f32_e32 v14, 1.0, v14
	v_add_f32_e32 v15, 1.0, v15
	v_add_f32_e32 v16, 1.0, v16
	v_add_f32_e32 v17, 1.0, v17
	v_pk_add_f32 v[8:9], v[8:9], v[64:65]
	v_pk_add_f32 v[6:7], v[6:7], v[62:63]
	v_pk_add_f32 v[4:5], v[4:5], v[60:61]
	v_pk_add_f32 v[2:3], v[2:3], v[58:59]
	v_mul_f32_e32 v6, 0xbfb8aa3b, v6
	v_mul_f32_e32 v7, 0xbfb8aa3b, v7
	v_mul_f32_e32 v8, 0xbfb8aa3b, v8
	v_mul_f32_e32 v9, 0xbfb8aa3b, v9
	v_mul_f32_e32 v2, 0xbfb8aa3b, v2
	v_mul_f32_e32 v3, 0xbfb8aa3b, v3
	v_mul_f32_e32 v4, 0xbfb8aa3b, v4
	v_mul_f32_e32 v5, 0xbfb8aa3b, v5
	v_exp_f32_e32 v6, v6
	v_exp_f32_e32 v7, v7
	v_exp_f32_e32 v8, v8
	v_exp_f32_e32 v9, v9
	v_exp_f32_e32 v2, v2
	v_exp_f32_e32 v3, v3
	v_exp_f32_e32 v4, v4
	v_exp_f32_e32 v5, v5
	v_add_f32_e32 v6, 1.0, v6
	v_add_f32_e32 v7, 1.0, v7
	v_add_f32_e32 v8, 1.0, v8
	v_add_f32_e32 v9, 1.0, v9
	s_nop 0
	s_waitcnt vmcnt(15)
	v_lshlrev_b32_e32 v98, 16, v232
	v_and_b32_e32 v99, 0xffff0000, v232
	v_lshlrev_b32_e32 v100, 16, v233
	v_and_b32_e32 v101, 0xffff0000, v233
	v_lshlrev_b32_e32 v102, 16, v234
	v_and_b32_e32 v103, 0xffff0000, v234
	v_lshlrev_b32_e32 v104, 16, v235
	v_and_b32_e32 v105, 0xffff0000, v235
	v_pk_mul_f32 v[96:97], v[96:97], v[104:105]
	v_pk_mul_f32 v[94:95], v[94:95], v[102:103]
	v_pk_mul_f32 v[100:101], v[92:93], v[100:101]
	v_pk_mul_f32 v[90:91], v[90:91], v[98:99]
	v_add_f32_e32 v104, 1.0, v82
	v_cvt_pk_bf16_f32 v92, v90, v91
	v_cvt_pk_bf16_f32 v93, v100, v101
	v_cvt_pk_bf16_f32 v94, v94, v95
	v_cvt_pk_bf16_f32 v95, v96, v97
	s_nop 0
	v_lshlrev_b64 v[100:101], 12, v[106:107]
	v_add_f32_e32 v105, 1.0, v83
	v_add_f32_e32 v106, 1.0, v84
	v_add_f32_e32 v107, 1.0, v85
	v_rcp_f32_e32 v82, v86
	v_rcp_f32_e32 v83, v87
	v_rcp_f32_e32 v84, v88
	v_rcp_f32_e32 v85, v89
	v_lshl_add_u64 v[100:101], s[4:5], 0, v[100:101]
	v_rcp_f32_e32 v86, v104
	v_rcp_f32_e32 v87, v105
	v_rcp_f32_e32 v88, v106
	v_rcp_f32_e32 v89, v107
	v_add_u32_e32 v90, 0x80, v168
	v_lshl_add_u64 v[100:101], v[100:101], 0, v[156:157]
	v_ashrrev_i32_e32 v91, 31, v90
	global_store_dwordx4 v[100:101], v[92:95], off
	v_lshlrev_b64 v[102:103], 10, v[90:91]
	v_lshl_add_u64 v[102:103], s[14:15], 0, v[102:103]
	v_lshl_add_u64 v[102:103], v[102:103], 0, v[156:157]
	s_nop 0
	s_waitcnt vmcnt(15)
	v_lshlrev_b32_e32 v92, 16, v236
	v_and_b32_e32 v93, 0xffff0000, v236
	v_lshlrev_b32_e32 v94, 16, v237
	v_and_b32_e32 v95, 0xffff0000, v237
	v_lshlrev_b32_e32 v96, 16, v238
	v_and_b32_e32 v97, 0xffff0000, v238
	v_lshlrev_b32_e32 v98, 16, v239
	v_and_b32_e32 v99, 0xffff0000, v239
	v_pk_mul_f32 v[84:85], v[84:85], v[94:95]
	v_pk_mul_f32 v[82:83], v[82:83], v[92:93]
	v_pk_mul_f32 v[88:89], v[88:89], v[98:99]
	v_pk_mul_f32 v[86:87], v[86:87], v[96:97]
	v_cvt_pk_bf16_f32 v82, v82, v83
	v_cvt_pk_bf16_f32 v83, v84, v85
	s_nop 0
	v_cvt_pk_bf16_f32 v84, v86, v87
	v_cvt_pk_bf16_f32 v85, v88, v89
	global_store_dwordx4 v[100:101], v[82:85], off offset:256
	s_nop 0
	v_add_f32_e32 v86, 1.0, v74
	v_add_f32_e32 v87, 1.0, v75
	v_add_f32_e32 v88, 1.0, v76
	v_add_f32_e32 v89, 1.0, v77
	v_rcp_f32_e32 v74, v78
	v_rcp_f32_e32 v75, v79
	v_rcp_f32_e32 v76, v80
	v_rcp_f32_e32 v77, v81
	v_rcp_f32_e32 v78, v86
	v_rcp_f32_e32 v79, v87
	v_rcp_f32_e32 v80, v88
	v_rcp_f32_e32 v81, v89
	s_nop 0
	s_waitcnt vmcnt(15)
; __device__ __forceinline__ f32x4 sigm4(f32x4 v) { return (f32x4){sigm(v[0]), sigm(v[1]), sigm(v[2]), sigm(v[3])}; }
; __device__ __forceinline__ f32x4 gelu4(f32x4 v) { return (f32x4){gelu_t(v[0]), gelu_t(v[1]), gelu_t(v[2]), gelu_t(v[3])}; }
; __device__ __forceinline__ u32x4 pack8(f32x4 a, f32x4 b) { u32x4 w; w.x = cvt_pk_bf16(a[0], a[1]); w.y = cvt_pk_bf16(a[2], a[3]); w.z = cvt_pk_bf16(b[0], b[1]); w.w = cvt_pk_bf16(b[2], b[3]); return w; }
; __device__ __forceinline__ void unpack8(u32x4 w, f32x4& a, f32x4& b) { a = (f32x4){bf_lo(w.x), bf_hi(w.x), bf_lo(w.y), bf_hi(w.y)}; b = (f32x4){bf_lo(w.z), bf_hi(w.z), bf_lo(w.w), bf_hi(w.w)}; }
;     __device__ __forceinline__ void operator()(const f32x4 (&acc)[2][2][4][2], const Unit& u, int wr, int wc, int fr, int fq) const {
;     ...
; #pragma unroll
;         for (int ai = 0; ai < 2; ++ai)
; #pragma unroll
;             for (int m = 0; m < 4; ++m) {
;                 const size_t row = (size_t)(row0 + ai * HALF + m * 16);
;                 float ssq = 0.f;
; #pragma unroll
;                 for (int bj = 0; bj < 2; ++bj) {
;                     const int col = col0 + bj * HALF;
;                     f32x4 v0 = acc[ai][bj][m][0], v1 = acc[ai][bj][m][1];
;                     if (MODE == EP_INPROJ) {
;                         const float rs = rsr[ai][m];
;                         v0 = v0 * rs; v1 = v1 * rs;
;                         if (kind == 1) { v0 = gelu4(v0); v1 = gelu4(v1); }
;                         else if (kind == 2) { v0 = sigm4(v0 + cb0[bj]); v1 = sigm4(v1 + cb1[bj]); }
;                         *(u32x4*)((bf16_t*)O + row * ldc + col) = pack8(v0, v1);
;                     } else if (MODE == EP_GLU) {
;                         f32x4 y0, y1; unpack8(*(const u32x4*)(aux + row * ldaux + col), y0, y1);
;                         v0 = y0 * sigm4(v0 + cb0[bj]); v1 = y1 * sigm4(v1 + cb1[bj]);
;                         *(u32x4*)((bf16_t*)O + row * ldc + col) = pack8(v0, v1);
	v_lshlrev_b32_e32 v86, 16, v206
	v_and_b32_e32 v87, 0xffff0000, v206
	v_lshlrev_b32_e32 v82, 16, v207
	v_and_b32_e32 v83, 0xffff0000, v207
	v_lshlrev_b32_e32 v88, 16, v208
	v_and_b32_e32 v89, 0xffff0000, v208
	v_lshlrev_b32_e32 v84, 16, v209
	v_and_b32_e32 v85, 0xffff0000, v209
	v_pk_mul_f32 v[82:83], v[76:77], v[82:83]
	v_pk_mul_f32 v[80:81], v[80:81], v[84:85]
	v_pk_mul_f32 v[78:79], v[78:79], v[88:89]
	v_pk_mul_f32 v[74:75], v[74:75], v[86:87]
	v_lshlrev_b64 v[84:85], 12, v[90:91]
	v_cvt_pk_bf16_f32 v76, v74, v75
	v_cvt_pk_bf16_f32 v77, v82, v83
	v_cvt_pk_bf16_f32 v78, v78, v79
	v_cvt_pk_bf16_f32 v79, v80, v81
	s_nop 0
	v_add_f32_e32 v88, 1.0, v50
	v_add_f32_e32 v89, 1.0, v51
	v_add_f32_e32 v90, 1.0, v52
	v_add_f32_e32 v91, 1.0, v53
	v_add_u32_e32 v74, 0x90, v168
	v_rcp_f32_e32 v50, v54
	v_rcp_f32_e32 v51, v55
	v_rcp_f32_e32 v52, v56
	v_rcp_f32_e32 v53, v57
	v_rcp_f32_e32 v54, v88
	v_rcp_f32_e32 v55, v89
	v_rcp_f32_e32 v56, v90
	v_rcp_f32_e32 v57, v91
	v_ashrrev_i32_e32 v75, 31, v74
	v_lshl_add_u64 v[84:85], s[4:5], 0, v[84:85]
	v_lshlrev_b64 v[86:87], 10, v[74:75]
	v_lshl_add_u64 v[84:85], v[84:85], 0, v[156:157]
	v_lshl_add_u64 v[86:87], s[14:15], 0, v[86:87]
	global_store_dwordx4 v[84:85], v[76:79], off
	v_lshl_add_u64 v[86:87], v[86:87], 0, v[156:157]
	s_nop 0
	s_waitcnt vmcnt(15)
	v_lshlrev_b32_e32 v76, 16, v246
	v_and_b32_e32 v77, 0xffff0000, v246
	v_lshlrev_b32_e32 v78, 16, v247
	v_and_b32_e32 v79, 0xffff0000, v247
	v_lshlrev_b32_e32 v80, 16, v248
	v_and_b32_e32 v81, 0xffff0000, v248
	v_lshlrev_b32_e32 v82, 16, v249
	v_and_b32_e32 v83, 0xffff0000, v249
	v_pk_mul_f32 v[52:53], v[52:53], v[78:79]
	v_pk_mul_f32 v[50:51], v[50:51], v[76:77]
	v_pk_mul_f32 v[56:57], v[56:57], v[82:83]
	v_pk_mul_f32 v[54:55], v[54:55], v[80:81]
	v_cvt_pk_bf16_f32 v50, v50, v51
	v_cvt_pk_bf16_f32 v51, v52, v53
	v_add_f32_e32 v76, 1.0, v42
	v_cvt_pk_bf16_f32 v52, v54, v55
	v_cvt_pk_bf16_f32 v53, v56, v57
	s_nop 0
	v_add_f32_e32 v77, 1.0, v43
	v_add_f32_e32 v78, 1.0, v44
	v_add_f32_e32 v79, 1.0, v45
	v_rcp_f32_e32 v42, v46
	v_rcp_f32_e32 v43, v47
	v_rcp_f32_e32 v44, v48
	v_rcp_f32_e32 v45, v49
	v_rcp_f32_e32 v46, v76
	v_rcp_f32_e32 v47, v77
	v_rcp_f32_e32 v48, v78
	v_rcp_f32_e32 v49, v79
	global_store_dwordx4 v[84:85], v[50:53], off offset:256
	s_nop 0
	s_nop 0
	s_waitcnt vmcnt(15)
	v_lshlrev_b32_e32 v50, 16, v188
	v_and_b32_e32 v51, 0xffff0000, v188
	v_lshlrev_b32_e32 v52, 16, v189
	v_and_b32_e32 v53, 0xffff0000, v189
	v_lshlrev_b32_e32 v54, 16, v190
	v_and_b32_e32 v55, 0xffff0000, v190
	v_lshlrev_b32_e32 v56, 16, v191
	v_and_b32_e32 v57, 0xffff0000, v191
	v_pk_mul_f32 v[48:49], v[48:49], v[56:57]
	v_pk_mul_f32 v[46:47], v[46:47], v[54:55]
	v_pk_mul_f32 v[52:53], v[44:45], v[52:53]
	v_pk_mul_f32 v[42:43], v[42:43], v[50:51]
	v_add_f32_e32 v56, 1.0, v34
	v_cvt_pk_bf16_f32 v44, v42, v43
	v_cvt_pk_bf16_f32 v45, v52, v53
	v_cvt_pk_bf16_f32 v46, v46, v47
	v_cvt_pk_bf16_f32 v47, v48, v49
	s_nop 0
	v_lshlrev_b64 v[52:53], 12, v[74:75]
	v_add_f32_e32 v57, 1.0, v35
	v_add_f32_e32 v74, 1.0, v36
	v_add_f32_e32 v75, 1.0, v37
	v_add_u32_e32 v42, 0xa0, v168
	v_rcp_f32_e32 v34, v38
	v_rcp_f32_e32 v35, v39
	v_rcp_f32_e32 v36, v40
	v_rcp_f32_e32 v37, v41
	v_rcp_f32_e32 v38, v56
	v_rcp_f32_e32 v39, v57
	v_rcp_f32_e32 v40, v74
	v_rcp_f32_e32 v41, v75
	v_ashrrev_i32_e32 v43, 31, v42
	v_lshl_add_u64 v[52:53], s[4:5], 0, v[52:53]
	v_lshlrev_b64 v[54:55], 10, v[42:43]
	v_lshl_add_u64 v[52:53], v[52:53], 0, v[156:157]
	v_lshl_add_u64 v[54:55], s[14:15], 0, v[54:55]
	global_store_dwordx4 v[52:53], v[44:47], off
	v_lshl_add_u64 v[54:55], v[54:55], 0, v[156:157]
	s_nop 0
	s_waitcnt vmcnt(14)
	v_lshlrev_b32_e32 v44, 16, v212
	v_and_b32_e32 v45, 0xffff0000, v212
	v_lshlrev_b32_e32 v46, 16, v213
	v_and_b32_e32 v47, 0xffff0000, v213
	v_lshlrev_b32_e32 v48, 16, v214
	v_and_b32_e32 v49, 0xffff0000, v214
	v_lshlrev_b32_e32 v50, 16, v215
	v_and_b32_e32 v51, 0xffff0000, v215
	v_pk_mul_f32 v[36:37], v[36:37], v[46:47]
	v_pk_mul_f32 v[34:35], v[34:35], v[44:45]
	v_pk_mul_f32 v[40:41], v[40:41], v[50:51]
	v_pk_mul_f32 v[38:39], v[38:39], v[48:49]
	v_cvt_pk_bf16_f32 v34, v34, v35
	v_cvt_pk_bf16_f32 v35, v36, v37
	v_add_f32_e32 v44, 1.0, v26
	v_cvt_pk_bf16_f32 v36, v38, v39
	v_cvt_pk_bf16_f32 v37, v40, v41
	s_nop 0
	v_add_f32_e32 v45, 1.0, v27
	v_add_f32_e32 v46, 1.0, v28
	v_add_f32_e32 v47, 1.0, v29
	v_rcp_f32_e32 v26, v30
	v_rcp_f32_e32 v27, v31
	v_rcp_f32_e32 v28, v32
	v_rcp_f32_e32 v29, v33
	v_rcp_f32_e32 v30, v44
	v_rcp_f32_e32 v31, v45
	v_rcp_f32_e32 v32, v46
	v_rcp_f32_e32 v33, v47
	global_store_dwordx4 v[52:53], v[34:37], off offset:256
	s_nop 0
	s_nop 0
	s_waitcnt vmcnt(13)
; __device__ __forceinline__ f32x4 sigm4(f32x4 v) { return (f32x4){sigm(v[0]), sigm(v[1]), sigm(v[2]), sigm(v[3])}; }
; __device__ __forceinline__ f32x4 gelu4(f32x4 v) { return (f32x4){gelu_t(v[0]), gelu_t(v[1]), gelu_t(v[2]), gelu_t(v[3])}; }
; __device__ __forceinline__ u32x4 pack8(f32x4 a, f32x4 b) { u32x4 w; w.x = cvt_pk_bf16(a[0], a[1]); w.y = cvt_pk_bf16(a[2], a[3]); w.z = cvt_pk_bf16(b[0], b[1]); w.w = cvt_pk_bf16(b[2], b[3]); return w; }
; __device__ __forceinline__ void unpack8(u32x4 w, f32x4& a, f32x4& b) { a = (f32x4){bf_lo(w.x), bf_hi(w.x), bf_lo(w.y), bf_hi(w.y)}; b = (f32x4){bf_lo(w.z), bf_hi(w.z), bf_lo(w.w), bf_hi(w.w)}; }
;     __device__ __forceinline__ void operator()(const f32x4 (&acc)[2][2][4][2], const Unit& u, int wr, int wc, int fr, int fq) const {
;     ...
; #pragma unroll
;         for (int ai = 0; ai < 2; ++ai)
; #pragma unroll
;             for (int m = 0; m < 4; ++m) {
;                 const size_t row = (size_t)(row0 + ai * HALF + m * 16);
;                 float ssq = 0.f;
; #pragma unroll
;                 for (int bj = 0; bj < 2; ++bj) {
;                     const int col = col0 + bj * HALF;
;                     f32x4 v0 = acc[ai][bj][m][0], v1 = acc[ai][bj][m][1];
;                     if (MODE == EP_INPROJ) {
;                         const float rs = rsr[ai][m];
;                         v0 = v0 * rs; v1 = v1 * rs;
;                         if (kind == 1) { v0 = gelu4(v0); v1 = gelu4(v1); }
;                         else if (kind == 2) { v0 = sigm4(v0 + cb0[bj]); v1 = sigm4(v1 + cb1[bj]); }
;                         *(u32x4*)((bf16_t*)O + row * ldc + col) = pack8(v0, v1);
;                     } else if (MODE == EP_GLU) {
;                         f32x4 y0, y1; unpack8(*(const u32x4*)(aux + row * ldaux + col), y0, y1);
;                         v0 = y0 * sigm4(v0 + cb0[bj]); v1 = y1 * sigm4(v1 + cb1[bj]);
;                         *(u32x4*)((bf16_t*)O + row * ldc + col) = pack8(v0, v1);
	v_lshlrev_b32_e32 v34, 16, v216
	v_and_b32_e32 v35, 0xffff0000, v216
	v_lshlrev_b32_e32 v36, 16, v217
	v_and_b32_e32 v37, 0xffff0000, v217
	v_lshlrev_b32_e32 v38, 16, v218
	v_and_b32_e32 v39, 0xffff0000, v218
	v_lshlrev_b32_e32 v40, 16, v219
	v_and_b32_e32 v41, 0xffff0000, v219
	v_pk_mul_f32 v[28:29], v[28:29], v[36:37]
	v_pk_mul_f32 v[26:27], v[26:27], v[34:35]
	v_pk_mul_f32 v[32:33], v[32:33], v[40:41]
	v_pk_mul_f32 v[30:31], v[30:31], v[38:39]
	v_cvt_pk_bf16_f32 v26, v26, v27
	v_cvt_pk_bf16_f32 v27, v28, v29
	v_lshlrev_b64 v[36:37], 12, v[42:43]
	v_cvt_pk_bf16_f32 v28, v30, v31
	v_cvt_pk_bf16_f32 v29, v32, v33
	s_nop 0
	v_add_f32_e32 v40, 1.0, v18
	v_add_f32_e32 v41, 1.0, v19
	v_add_f32_e32 v42, 1.0, v20
	v_add_f32_e32 v43, 1.0, v21
	v_add_u32_e32 v34, 0xb0, v168
	v_rcp_f32_e32 v18, v22
	v_rcp_f32_e32 v19, v23
	v_rcp_f32_e32 v20, v24
	v_rcp_f32_e32 v21, v25
	v_rcp_f32_e32 v22, v40
	v_rcp_f32_e32 v23, v41
	v_rcp_f32_e32 v24, v42
	v_rcp_f32_e32 v25, v43
	v_ashrrev_i32_e32 v35, 31, v34
	v_lshl_add_u64 v[36:37], s[4:5], 0, v[36:37]
	v_lshlrev_b64 v[38:39], 10, v[34:35]
	v_lshl_add_u64 v[36:37], v[36:37], 0, v[156:157]
	v_lshl_add_u64 v[38:39], s[14:15], 0, v[38:39]
	global_store_dwordx4 v[36:37], v[26:29], off
	v_lshl_add_u64 v[38:39], v[38:39], 0, v[156:157]
	s_nop 0
	s_waitcnt vmcnt(12)
	v_lshlrev_b32_e32 v26, 16, v220
	v_and_b32_e32 v27, 0xffff0000, v220
	v_lshlrev_b32_e32 v28, 16, v221
	v_and_b32_e32 v29, 0xffff0000, v221
	v_lshlrev_b32_e32 v30, 16, v222
	v_and_b32_e32 v31, 0xffff0000, v222
	v_lshlrev_b32_e32 v32, 16, v223
	v_and_b32_e32 v33, 0xffff0000, v223
	v_pk_mul_f32 v[20:21], v[20:21], v[28:29]
	v_pk_mul_f32 v[18:19], v[18:19], v[26:27]
	v_pk_mul_f32 v[24:25], v[24:25], v[32:33]
	v_pk_mul_f32 v[22:23], v[22:23], v[30:31]
	v_cvt_pk_bf16_f32 v18, v18, v19
	v_cvt_pk_bf16_f32 v19, v20, v21
	v_add_f32_e32 v26, 1.0, v10
	v_cvt_pk_bf16_f32 v20, v22, v23
	v_cvt_pk_bf16_f32 v21, v24, v25
	s_nop 0
	v_add_f32_e32 v27, 1.0, v11
	v_add_f32_e32 v28, 1.0, v12
	v_add_f32_e32 v29, 1.0, v13
	v_rcp_f32_e32 v10, v14
	v_rcp_f32_e32 v11, v15
	v_rcp_f32_e32 v12, v16
	v_rcp_f32_e32 v13, v17
	v_rcp_f32_e32 v14, v26
	v_rcp_f32_e32 v15, v27
	v_rcp_f32_e32 v16, v28
	v_rcp_f32_e32 v17, v29
	global_store_dwordx4 v[36:37], v[18:21], off offset:256
	s_nop 0
	s_nop 0
	s_waitcnt vmcnt(11)
	v_lshlrev_b32_e32 v18, 16, v224
	v_and_b32_e32 v19, 0xffff0000, v224
	v_lshlrev_b32_e32 v20, 16, v225
	v_and_b32_e32 v21, 0xffff0000, v225
	v_lshlrev_b32_e32 v22, 16, v226
	v_and_b32_e32 v23, 0xffff0000, v226
	v_lshlrev_b32_e32 v24, 16, v227
	v_and_b32_e32 v25, 0xffff0000, v227
	v_pk_mul_f32 v[12:13], v[12:13], v[20:21]
	v_pk_mul_f32 v[10:11], v[10:11], v[18:19]
	v_pk_mul_f32 v[16:17], v[16:17], v[24:25]
	v_pk_mul_f32 v[14:15], v[14:15], v[22:23]
	v_cvt_pk_bf16_f32 v10, v10, v11
	v_cvt_pk_bf16_f32 v11, v12, v13
	v_lshlrev_b64 v[18:19], 12, v[34:35]
	v_cvt_pk_bf16_f32 v12, v14, v15
	v_cvt_pk_bf16_f32 v13, v16, v17
	s_nop 0
	v_add_f32_e32 v20, 1.0, v2
	v_add_f32_e32 v21, 1.0, v3
	v_add_f32_e32 v22, 1.0, v4
	v_add_f32_e32 v23, 1.0, v5
	v_rcp_f32_e32 v2, v6
	v_rcp_f32_e32 v3, v7
	v_rcp_f32_e32 v4, v8
	v_rcp_f32_e32 v5, v9
	v_lshl_add_u64 v[18:19], s[4:5], 0, v[18:19]
	v_rcp_f32_e32 v6, v20
	v_rcp_f32_e32 v7, v21
	v_rcp_f32_e32 v8, v22
	v_rcp_f32_e32 v9, v23
	v_lshl_add_u64 v[18:19], v[18:19], 0, v[156:157]
	global_store_dwordx4 v[18:19], v[10:13], off
	s_nop 0
	s_nop 0
	s_waitcnt vmcnt(10)
	v_lshlrev_b32_e32 v10, 16, v228
	v_and_b32_e32 v11, 0xffff0000, v228
	v_lshlrev_b32_e32 v12, 16, v229
	v_and_b32_e32 v13, 0xffff0000, v229
	v_lshlrev_b32_e32 v14, 16, v230
	v_and_b32_e32 v15, 0xffff0000, v230
	v_lshlrev_b32_e32 v16, 16, v231
	v_and_b32_e32 v17, 0xffff0000, v231
	v_pk_mul_f32 v[4:5], v[4:5], v[12:13]
	v_pk_mul_f32 v[2:3], v[2:3], v[10:11]
	v_pk_mul_f32 v[8:9], v[8:9], v[16:17]
	v_pk_mul_f32 v[6:7], v[6:7], v[14:15]
	v_cvt_pk_bf16_f32 v2, v2, v3
	v_cvt_pk_bf16_f32 v3, v4, v5
	s_nop 0
	v_cvt_pk_bf16_f32 v4, v6, v7
	v_cvt_pk_bf16_f32 v5, v8, v9
	global_store_dwordx4 v[18:19], v[2:5], off offset:256
	s_cbranch_vccnz .LBB0_120
	s_andn2_b64 vcc, exec, s[2:3]
	s_cbranch_vccnz .LBB0_119
	s_barrier
	s_branch .LBB0_119

; __device__ __forceinline__ void ssm_pass3h(CArgs* ap, const float* COEF, int l, const bf16_t* PROJ, const float* SST, bf16_t* YS, LAS unsigned char* wlds, int unit, int lane) {
;     ...
;         for (int q = 0; q < 4; ++q) {
;             const int t = 16 * blk + 4 * q;
;             u32x4 wc[8];
; #pragma unroll
;             for (int j = 0; j < 8; ++j) wc[j] = wn[j];
;             const int tn = (t + 4 < 128) ? t + 4 : t;
; #pragma unroll
;             for (int tt = 0; tt < 4; ++tt) { wn[2 * tt] = ((const u32x4*)(up + (size_t)(tn + tt) * INW))[0]; wn[2 * tt + 1] = ((const u32x4*)(up + (size_t)(tn + tt) * INW))[1]; }
; #pragma unroll
;             for (int tt = 0; tt < 4; ++tt) {
;                 const u32x4 w0 = wc[2 * tt], w1 = wc[2 * tt + 1];
;                 const unsigned u2[8] = {w0.x, w0.y, w0.z, w0.w, w1.x, w1.y, w1.z, w1.w};
;                 float br_ = 0.f, bi_ = 0.f;
; #pragma unroll
;                 for (int k = 0; k < 8; ++k) { br_ = __builtin_amdgcn_fdot2_f32_bf16(__builtin_bit_cast(bf16x2v, bbr2[k]), __builtin_bit_cast(bf16x2v, u2[k]), br_, false);
;                                                bi_ = __builtin_amdgcn_fdot2_f32_bf16(__builtin_bit_cast(bf16x2v, bbi2[k]), __builtin_bit_cast(bf16x2v, u2[k]), bi_, false); }
;                 const float nr = abr * hr - abi * hi + br_, ni = abr * hi + abi * hr + bi_; hr = nr; hi = ni;
;                 Hf[(4 * q + tt) * 132 + lane] = hr; Hf[(4 * q + tt) * 132 + 64 + lane] = hi;
;             }
.LBB0_150:
	s_add_i32 s13, s14, 4
	s_cmpk_lt_u32 s14, 0x7c
	s_cselect_b32 s14, s13, s14
	s_mul_i32 s78, s14, 0x2400
	s_lshl_b64 s[14:15], s[78:79], 1
	s_add_u32 s14, s2, s14
	s_waitcnt vmcnt(7)
	v_mov_b64_e32 v[138:139], v[22:23]
	s_waitcnt vmcnt(6)
	v_mov_b64_e32 v[142:143], v[26:27]
	s_addc_u32 s15, s3, s15
	v_mov_b64_e32 v[136:137], v[20:21]
	v_mov_b64_e32 v[140:141], v[24:25]
	global_load_dwordx4 v[20:23], v1, s[14:15] offset:16
	global_load_dwordx4 v[24:27], v1, s[14:15]
	s_add_i32 s14, s78, 0x2400
	s_mov_b32 s15, s79
	s_lshl_b64 s[14:15], s[14:15], 1
	s_add_u32 s14, s2, s14
	s_waitcnt vmcnt(7)
	v_mov_b64_e32 v[70:71], v[30:31]
	s_waitcnt vmcnt(6)
	v_mov_b64_e32 v[74:75], v[34:35]
	s_addc_u32 s15, s3, s15
	v_mov_b64_e32 v[68:69], v[28:29]
	v_mov_b64_e32 v[72:73], v[32:33]
	global_load_dwordx4 v[28:31], v1, s[14:15] offset:16
	global_load_dwordx4 v[32:35], v1, s[14:15]
	s_add_i32 s14, s78, 0x4800
	s_mov_b32 s15, s79
	s_lshl_b64 s[14:15], s[14:15], 1
	s_add_u32 s14, s2, s14
	s_waitcnt vmcnt(7)
	v_mov_b64_e32 v[62:63], v[38:39]
	s_waitcnt vmcnt(6)
	v_mov_b64_e32 v[66:67], v[42:43]
	s_addc_u32 s15, s3, s15
	s_addk_i32 s78, 0x6c00
	v_mov_b64_e32 v[60:61], v[36:37]
	v_mov_b64_e32 v[64:65], v[40:41]
	global_load_dwordx4 v[36:39], v1, s[14:15] offset:16
	global_load_dwordx4 v[40:43], v1, s[14:15]
	s_lshl_b64 s[14:15], s[78:79], 1
	s_add_u32 s14, s2, s14
	s_waitcnt vmcnt(7)
	v_mov_b64_e32 v[54:55], v[46:47]
	s_waitcnt vmcnt(6)
	v_mov_b64_e32 v[58:59], v[50:51]
	s_addc_u32 s15, s3, s15
	v_mov_b64_e32 v[52:53], v[44:45]
	v_mov_b64_e32 v[56:57], v[48:49]
	global_load_dwordx4 v[44:47], v1, s[14:15] offset:16
	global_load_dwordx4 v[48:51], v1, s[14:15]
	v_mov_b32_e32 v0, 0
	v_dot2c_f32_bf16_e32 v0, v101, v140
	v_mov_b32_e32 v97, 0
	v_dot2c_f32_bf16_e32 v97, v102, v140
	v_dot2c_f32_bf16_e32 v0, v103, v141
	v_dot2c_f32_bf16_e32 v97, v104, v141
	v_dot2c_f32_bf16_e32 v0, v105, v142
	v_dot2c_f32_bf16_e32 v97, v106, v142
	v_dot2c_f32_bf16_e32 v0, v107, v143
	v_dot2c_f32_bf16_e32 v97, v108, v143
	v_dot2c_f32_bf16_e32 v0, v109, v136
	v_dot2c_f32_bf16_e32 v97, v110, v136
	v_dot2c_f32_bf16_e32 v0, v111, v137
	v_dot2c_f32_bf16_e32 v97, v112, v137
	v_dot2c_f32_bf16_e32 v0, v113, v138
	v_pk_mul_f32 v[136:137], v[2:3], v[90:91]
	v_dot2c_f32_bf16_e32 v0, v115, v139
	v_sub_f32_e32 v136, v136, v137
	v_mov_b32_e32 v137, 0
	v_dot2c_f32_bf16_e32 v137, v102, v72
	v_add_f32_e32 v0, v0, v136
	v_mov_b32_e32 v136, 0
	v_dot2c_f32_bf16_e32 v136, v101, v72
	v_dot2c_f32_bf16_e32 v136, v103, v73
	v_dot2c_f32_bf16_e32 v137, v104, v73
	v_dot2c_f32_bf16_e32 v136, v105, v74
	v_dot2c_f32_bf16_e32 v137, v106, v74
	v_dot2c_f32_bf16_e32 v136, v107, v75
	v_dot2c_f32_bf16_e32 v137, v108, v75
	v_dot2c_f32_bf16_e32 v136, v109, v68
	v_dot2c_f32_bf16_e32 v137, v110, v68
	v_dot2c_f32_bf16_e32 v136, v111, v69
	v_dot2c_f32_bf16_e32 v137, v112, v69
	v_mov_b32_e32 v68, 0
	v_mov_b32_e32 v69, 0
	v_dot2c_f32_bf16_e32 v68, v101, v64
	v_dot2c_f32_bf16_e32 v69, v102, v64
	v_dot2c_f32_bf16_e32 v68, v103, v65
	v_dot2c_f32_bf16_e32 v69, v104, v65
	v_dot2c_f32_bf16_e32 v68, v105, v66
	v_dot2c_f32_bf16_e32 v69, v106, v66
	v_dot2c_f32_bf16_e32 v97, v114, v138
	v_pk_mul_f32 v[90:91], v[94:95], v[90:91]
	v_dot2c_f32_bf16_e32 v68, v107, v67
	v_dot2c_f32_bf16_e32 v69, v108, v67
	v_dot2c_f32_bf16_e32 v97, v116, v139
	v_add_f32_e32 v90, v90, v91
	v_dot2c_f32_bf16_e32 v68, v109, v60
	v_dot2c_f32_bf16_e32 v69, v110, v60
	v_add_f32_e32 v90, v97, v90
	v_dot2c_f32_bf16_e32 v68, v111, v61
	v_dot2c_f32_bf16_e32 v69, v112, v61
	v_dot2c_f32_bf16_e32 v68, v113, v62
	v_dot2c_f32_bf16_e32 v69, v114, v62
	v_pk_mul_f32 v[60:61], v[94:95], v[90:91] op_sel_hi:[1,0]
	v_dot2c_f32_bf16_e32 v136, v113, v70
	v_dot2c_f32_bf16_e32 v137, v114, v70
	v_dot2c_f32_bf16_e32 v68, v115, v63
	v_dot2c_f32_bf16_e32 v69, v116, v63
	v_pk_fma_f32 v[62:63], v[2:3], v[0:1], v[60:61] neg_lo:[0,0,1] neg_hi:[0,0,1]
	v_pk_fma_f32 v[60:61], v[2:3], v[0:1], v[60:61] op_sel_hi:[1,0,1]
	v_dot2c_f32_bf16_e32 v136, v115, v71
	v_dot2c_f32_bf16_e32 v137, v116, v71
	v_mov_b32_e32 v63, v61
	v_add_u32_e32 v97, s12, v99
	ds_write2st64_b32 v97, v0, v90 offset1:1
	v_pk_add_f32 v[60:61], v[136:137], v[62:63]
	ds_write2_b32 v97, v60, v61 offset0:132 offset1:196
	v_pk_mul_f32 v[62:63], v[2:3], v[60:61]
	v_pk_mul_f32 v[60:61], v[2:3], v[60:61] op_sel:[0,1] op_sel_hi:[1,0]
	v_sub_f32_e32 v0, v62, v63
	v_mov_b32_e32 v62, 0
	v_mov_b32_e32 v63, 0
	v_dot2c_f32_bf16_e32 v62, v101, v56
	v_dot2c_f32_bf16_e32 v63, v102, v56
	v_dot2c_f32_bf16_e32 v62, v103, v57
	v_dot2c_f32_bf16_e32 v63, v104, v57
	v_dot2c_f32_bf16_e32 v62, v105, v58
	v_dot2c_f32_bf16_e32 v63, v106, v58
	v_dot2c_f32_bf16_e32 v62, v107, v59
	v_dot2c_f32_bf16_e32 v63, v108, v59
	v_add_f32_e32 v60, v60, v61
	v_dot2c_f32_bf16_e32 v62, v109, v52
	v_dot2c_f32_bf16_e32 v63, v110, v52
	v_add_f32_e32 v60, v69, v60
	v_add_u32_e32 v61, 32, v97
	v_dot2c_f32_bf16_e32 v62, v111, v53
	v_dot2c_f32_bf16_e32 v63, v112, v53
	v_add_f32_e32 v0, v68, v0
	v_dot2c_f32_bf16_e32 v62, v113, v54
	v_dot2c_f32_bf16_e32 v63, v114, v54
	v_pk_mul_f32 v[52:53], v[94:95], v[60:61] op_sel_hi:[1,0]
	v_dot2c_f32_bf16_e32 v62, v115, v55
	v_dot2c_f32_bf16_e32 v63, v116, v55
	v_pk_fma_f32 v[54:55], v[2:3], v[0:1], v[52:53] neg_lo:[0,0,1] neg_hi:[0,0,1]
	v_pk_fma_f32 v[52:53], v[2:3], v[0:1], v[52:53] op_sel_hi:[1,0,1]
	s_addk_i32 s12, 0x840
	v_mov_b32_e32 v55, v53
	ds_write2st64_b32 v61, v0, v60 offset0:4 offset1:5
	v_pk_add_f32 v[90:91], v[62:63], v[54:55]
	v_add_u32_e32 v0, 48, v97
	s_cmpk_eq_i32 s12, 0x2100
	s_mov_b32 s14, s13
	ds_write2st64_b32 v0, v90, v91 offset0:6 offset1:7
	s_cbranch_scc0 .LBB0_150
; __device__ __forceinline__ float gelu_t(float x) { const float p = __builtin_fmaf(x * x, -0.10294324f, -2.30220819f); return x * __builtin_amdgcn_rcpf(1.f + __builtin_amdgcn_exp2f(x * p)); }
; #define LAS __attribute__((address_space(3)))
; __device__ __forceinline__ unsigned f2bf(float f) { unsigned u = __builtin_bit_cast(unsigned, f); return (u + 0x7fffu + ((u >> 16) & 1u)) >> 16; }
; __device__ __forceinline__ void ssm_pass3h(CArgs* ap, const float* COEF, int l, const bf16_t* PROJ, const float* SST, bf16_t* YS, LAS unsigned char* wlds, int unit, int lane) {
;     ...
;         asm volatile("s_waitcnt lgkmcnt(0)" ::: "memory");
;         f32x4 y = (f32x4){0.f, 0.f, 0.f, 0.f};
; #pragma unroll
;         for (int j = 0; j < 8; ++j) {
;             const f32x4 a4 = *(const LAS f32x4*)(Hf + fr * 132 + 16 * j + 4 * fq);
; #pragma unroll
;             for (int r = 0; r < 4; ++r) y = __builtin_amdgcn_mfma_f32_16x16x4f32(a4[r], cmB[4 * j + r], y, 0, 0, 0);
;         }
;         asm volatile("s_waitcnt lgkmcnt(0)" ::: "memory");
; #pragma unroll
;         for (int i = 0; i < 4; ++i) {
;             const size_t row = row0 + 16 * blk + 4 * fq + i;
;             YS[row * 512 + g * 16 + fr] = (bf16_t)f2bf(gelu_t(y[i] + dsk * __uint_as_float(((unsigned)uq[i]) << 16)));
;         }
	s_waitcnt lgkmcnt(0)
	ds_read_b128 v[144:147], v100
	ds_read_b128 v[148:151], v100 offset:64
	ds_read_b128 v[152:155], v100 offset:128
	ds_read_b128 v[168:171], v100 offset:192
	ds_read_b128 v[172:175], v100 offset:256
	ds_read_b128 v[176:179], v100 offset:320
	ds_read_b128 v[180:183], v100 offset:384
	ds_read_b128 v[184:187], v100 offset:448
	s_waitcnt vmcnt(11)
	v_lshlrev_b32_e32 v57, 16, v135
	v_mov_b32_e32 v97, v1
	v_or_b32_e32 v0, 1, v96
	v_or_b32_e32 v58, 2, v96
	v_mov_b32_e32 v59, v1
	v_or_b32_e32 v56, 3, v96
	s_add_i32 s11, s11, 1
	s_add_i32 s10, s10, 16
	s_cmp_eq_u32 s11, 8
	v_lshl_add_u64 v[60:61], v[96:97], 0, s[0:1]
	v_lshlrev_b64 v[60:61], 10, v[60:61]
	v_lshl_add_u64 v[60:61], v[92:93], 0, v[60:61]
	s_waitcnt lgkmcnt(6)
	v_mfma_f32_16x16x4_f32 v[52:55], v144, v4, 0
	v_mfma_f32_16x16x4_f32 v[188:191], v148, v8, 0
	v_mfma_f32_16x16x4_f32 v[52:55], v145, v5, v[52:55]
	v_mfma_f32_16x16x4_f32 v[188:191], v149, v9, v[188:191]
	v_mfma_f32_16x16x4_f32 v[52:55], v146, v6, v[52:55]
	v_mfma_f32_16x16x4_f32 v[188:191], v150, v10, v[188:191]
	v_mfma_f32_16x16x4_f32 v[52:55], v147, v7, v[52:55]
	v_mfma_f32_16x16x4_f32 v[188:191], v151, v11, v[188:191]
	s_waitcnt lgkmcnt(4)
	v_mfma_f32_16x16x4_f32 v[52:55], v152, v12, v[52:55]
	v_mfma_f32_16x16x4_f32 v[188:191], v168, v16, v[188:191]
	v_mfma_f32_16x16x4_f32 v[52:55], v153, v13, v[52:55]
	v_mfma_f32_16x16x4_f32 v[188:191], v169, v17, v[188:191]
	v_mfma_f32_16x16x4_f32 v[52:55], v154, v14, v[52:55]
	v_mfma_f32_16x16x4_f32 v[188:191], v170, v18, v[188:191]
	v_mfma_f32_16x16x4_f32 v[52:55], v155, v15, v[52:55]
	v_mfma_f32_16x16x4_f32 v[188:191], v171, v19, v[188:191]
	s_waitcnt lgkmcnt(2)
	v_mfma_f32_16x16x4_f32 v[52:55], v172, v89, v[52:55]
	v_mfma_f32_16x16x4_f32 v[188:191], v176, v120, v[188:191]
	v_mfma_f32_16x16x4_f32 v[52:55], v173, v117, v[52:55]
	v_mfma_f32_16x16x4_f32 v[188:191], v177, v121, v[188:191]
	v_mfma_f32_16x16x4_f32 v[52:55], v174, v118, v[52:55]
	v_mfma_f32_16x16x4_f32 v[188:191], v178, v122, v[188:191]
	v_mfma_f32_16x16x4_f32 v[52:55], v175, v119, v[52:55]
	v_mfma_f32_16x16x4_f32 v[188:191], v179, v123, v[188:191]
	s_waitcnt lgkmcnt(0)
	v_mfma_f32_16x16x4_f32 v[52:55], v180, v124, v[52:55]
	v_mfma_f32_16x16x4_f32 v[188:191], v184, v128, v[188:191]
	v_mfma_f32_16x16x4_f32 v[52:55], v181, v125, v[52:55]
	v_mfma_f32_16x16x4_f32 v[188:191], v185, v129, v[188:191]
	v_mfma_f32_16x16x4_f32 v[52:55], v182, v126, v[52:55]
	v_mfma_f32_16x16x4_f32 v[188:191], v186, v130, v[188:191]
	v_mfma_f32_16x16x4_f32 v[52:55], v183, v127, v[52:55]
	v_mfma_f32_16x16x4_f32 v[188:191], v187, v131, v[188:191]
	s_nop 9
	s_nop 1
	v_add_f32_e32 v52, v52, v188
	v_add_f32_e32 v53, v53, v189
	v_add_f32_e32 v54, v54, v190
	v_add_f32_e32 v55, v55, v191
	v_fma_f32 v52, v87, v57, v52
	v_mul_f32_e32 v57, v52, v52
	v_fmamk_f32 v57, v57, 0xbdd2d3e8, v196
	v_mul_f32_e32 v57, v52, v57
	v_exp_f32_e32 v57, v57
	s_nop 0
	v_add_f32_e32 v57, 1.0, v57
	v_rcp_f32_e32 v57, v57
	s_nop 0
	v_mul_f32_e32 v52, v52, v57
	v_bfe_u32 v57, v52, 16, 1
	v_add3_u32 v52, v52, v57, s80
	global_store_short_d16_hi v[60:61], v52, off
	v_lshl_add_u64 v[60:61], v[0:1], 0, s[0:1]
	s_waitcnt vmcnt(11)
	v_lshlrev_b32_e32 v0, 16, v134
	v_fma_f32 v0, v87, v0, v53
	v_mul_f32_e32 v52, v0, v0
	v_fmamk_f32 v52, v52, 0xbdd2d3e8, v196
	v_mul_f32_e32 v52, v0, v52
	v_exp_f32_e32 v52, v52
	v_mov_b32_e32 v57, v1
	v_add_f32_e32 v52, 1.0, v52
	v_rcp_f32_e32 v52, v52
	s_nop 0
	v_mul_f32_e32 v0, v0, v52
	v_bfe_u32 v52, v0, 16, 1
	v_add3_u32 v0, v0, v52, s80
	v_lshlrev_b64 v[52:53], 10, v[60:61]
	v_lshl_add_u64 v[52:53], v[92:93], 0, v[52:53]
	global_store_short_d16_hi v[52:53], v0, off
	s_waitcnt vmcnt(11)
	v_lshlrev_b32_e32 v0, 16, v133
	v_fma_f32 v0, v87, v0, v54
	v_mul_f32_e32 v54, v0, v0
	v_fmamk_f32 v54, v54, 0xbdd2d3e8, v196
	v_mul_f32_e32 v54, v0, v54
	v_exp_f32_e32 v54, v54
	v_lshl_add_u64 v[52:53], v[58:59], 0, s[0:1]
	v_lshlrev_b64 v[52:53], 10, v[52:53]
	v_lshl_add_u64 v[52:53], v[92:93], 0, v[52:53]
	v_add_f32_e32 v54, 1.0, v54
	v_rcp_f32_e32 v54, v54
	s_nop 0
	v_mul_f32_e32 v0, v0, v54
	v_bfe_u32 v54, v0, 16, 1
	v_add3_u32 v0, v0, v54, s80
	global_store_short_d16_hi v[52:53], v0, off
	s_waitcnt vmcnt(11)
	v_lshlrev_b32_e32 v0, 16, v132
	v_fmac_f32_e32 v55, v87, v0
	v_mul_f32_e32 v0, v55, v55
	v_fmamk_f32 v0, v0, 0xbdd2d3e8, v196
	v_mul_f32_e32 v0, v55, v0
	v_exp_f32_e32 v0, v0
	v_lshl_add_u64 v[52:53], v[56:57], 0, s[0:1]
	v_lshlrev_b64 v[52:53], 10, v[52:53]
	v_lshl_add_u64 v[52:53], v[92:93], 0, v[52:53]
	v_add_f32_e32 v0, 1.0, v0
	v_rcp_f32_e32 v0, v0
	s_nop 0
	v_mul_f32_e32 v0, v55, v0
	v_bfe_u32 v54, v0, 16, 1
	v_add3_u32 v0, v0, v54, s80
	global_store_short_d16_hi v[52:53], v0, off
	s_cbranch_scc0 .LBB0_149
	s_add_i32 s9, s9, s33
	s_cmpk_gt_i32 s9, 0xfff
	s_cbranch_scc0 .LBB0_141
